# window / memory attention unit prologues: the four Q-tile loads are issued together with the first K/V loads instead of load-wait-write serially
# baseline (speedup 1.0000x reference)
.LBB0_742:
	s_mov_b64 s[0:1], s[56:57]
	v_mov_b32_e32 v1, v0
	s_load_dwordx2 s[4:5], s[0:1], 0xf0
	v_readlane_b32 s0, v252, 8
	v_mbcnt_lo_u32_b32 v1, -1, v1
	v_mbcnt_hi_u32_b32 v1, -1, v1
	v_add_u32_e32 v1, s0, v1
	s_mov_b64 s[12:13], s[56:57]
	s_ashr_i32 s0, s11, 5
	s_load_dwordx2 s[12:13], s[12:13], 0xf0
	s_lshl_b32 s14, s0, 11
	s_mul_i32 s15, s0, 0x3000000
	s_mul_hi_i32 s14, s14, 0x6000
	s_waitcnt lgkmcnt(0)
	s_add_u32 s15, s4, s15
	s_addc_u32 s14, s5, s14
	s_lshl_b32 s4, s0, 8
	s_ashr_i32 s5, s4, 31
	s_and_b32 s16, s3, 0xc0
	s_lshl_b64 s[4:5], s[4:5], 12
	s_add_u32 s4, s12, s4
	s_addc_u32 s5, s13, s5
	s_lshl_b32 s12, s22, 1
	s_add_u32 s4, s4, s12
	s_addc_u32 s5, s5, 0
	s_lshl_b32 s36, s16, 1
	s_add_u32 s4, s4, s36
	s_addc_u32 s5, s5, 0
	v_readfirstlane_b32 s1, v1
	s_add_u32 s4, s4, 0x3f500000
	s_addc_u32 s5, s5, 0
	s_ashr_i32 s13, s1, 1
	s_and_b32 s12, s10, 0x700
	s_andn2_b32 s13, s13, 31
	s_add_i32 s16, s13, s12
	s_add_u32 s12, s15, s36
	s_addc_u32 s13, s14, 0
	s_add_u32 s12, s12, 0x3fd03e00
	s_addc_u32 s13, s13, 0
	v_and_or_b32 v78, v1, 31, s16
	v_mov_b64_e32 v[2:3], s[12:13]
	s_movk_i32 s12, 0x6000
	v_bfe_u32 v4, v1, 5, 1
	v_mad_i64_i32 v[2:3], s[12:13], v78, s12, v[2:3]
	v_lshlrev_b32_e32 v6, 4, v4
	v_mov_b32_e32 v7, v0
	v_lshl_add_u64 v[2:3], v[2:3], 0, v[6:7]
	global_load_dwordx4 v[164:167], v[2:3], off
	global_load_dwordx4 v[148:151], v[2:3], off offset:32
	global_load_dwordx4 v[152:155], v[2:3], off offset:64
	global_load_dwordx4 v[156:159], v[2:3], off offset:96
	s_ashr_i32 s1, s1, 6
	s_lshl_b32 s12, s1, 12
	v_and_b32_e32 v5, 63, v1
	s_add_i32 s12, s12, 0
	s_add_i32 s12, s12, 0x1a980
	v_lshlrev_b32_e32 v5, 4, v5
	v_add_u32_e32 v79, s12, v5
	v_lshlrev_b32_e32 v5, 4, v1
	v_xor_b32_e32 v5, v5, v1
	s_cmp_lt_i32 s1, 4
	v_ashrrev_i32_e32 v2, 3, v1
	v_lshlrev_b32_e32 v3, 7, v2
	v_and_or_b32 v5, v5, s40, v3
	v_ashrrev_i32_e32 v3, 31, v2
	v_lshlrev_b64 v[2:3], 12, v[2:3]
	v_lshl_add_u64 v[2:3], s[4:5], 0, v[2:3]
	v_add_u32_e32 v87, 0, v5
	v_lshlrev_b32_e32 v6, 3, v1
	v_and_b32_e32 v6, 56, v6
	v_lshlrev_b32_e32 v6, 1, v6
	v_mov_b32_e32 v7, v0
	v_lshl_add_u64 v[42:43], v[2:3], 0, v[6:7]
	v_ashrrev_i32_e32 v2, 31, v1
	v_lshrrev_b32_e32 v2, 29, v2
	v_add_u32_e32 v2, v1, v2
	v_ashrrev_i32_e32 v18, 3, v2
	v_and_b32_e32 v2, -8, v2
	v_sub_u32_e32 v22, v1, v2
	v_ashrrev_i32_e32 v19, 31, v18
	global_load_dwordx4 v[6:9], v[42:43], off
	v_lshlrev_b64 v[44:45], 12, v[18:19]
	v_lshlrev_b32_e32 v2, 3, v22
	v_lshl_add_u64 v[10:11], s[4:5], 0, v[44:45]
	v_ashrrev_i32_e32 v3, 31, v2
	v_lshl_add_u64 v[20:21], v[2:3], 1, v[10:11]
	v_add_co_u32_e32 v14, vcc, s67, v42
	global_load_dwordx4 v[10:13], v[20:21], off offset:512
	s_nop 0
	v_addc_co_u32_e32 v15, vcc, 0, v43, vcc
	global_load_dwordx4 v[14:17], v[14:15], off
	v_mul_lo_u32 v5, v18, s34
	v_add_u32_e32 v5, 0, v5
	s_waitcnt vmcnt(6)
	ds_write_b128 v79, v[164:167]
	s_waitcnt vmcnt(5)
	ds_write_b128 v79, v[148:151] offset:1024
	s_waitcnt vmcnt(4)
	ds_write_b128 v79, v[152:155] offset:2048
	s_waitcnt vmcnt(3)
	ds_write_b128 v79, v[156:159] offset:3072
	s_waitcnt vmcnt(2)
	ds_write_b128 v87, v[6:9]
	v_lshlrev_b32_e32 v6, 4, v22
	v_add_u32_e32 v81, v5, v6
	v_add_co_u32_e32 v6, vcc, 0x80000, v42
	s_waitcnt vmcnt(1)
	ds_write_b128 v81, v[10:13] offset:24576
	s_waitcnt vmcnt(0)
	ds_write_b128 v87, v[14:17] offset:8192
	v_addc_co_u32_e32 v7, vcc, 0, v43, vcc
	s_waitcnt lgkmcnt(0)
	s_barrier
	global_load_dwordx4 v[34:37], v[6:7], off
	v_add_co_u32_e32 v6, vcc, 0x40000, v20
	s_nop 1
	v_addc_co_u32_e32 v7, vcc, 0, v21, vcc
	global_load_dwordx4 v[38:41], v[6:7], off offset:512
	s_cbranch_scc1 .LBB0_744
	s_barrier

.LBB0_797:
	s_or_b64 exec, exec, s[4:5]
	s_cmpk_gt_u32 s3, 0x3ff
	s_mov_b64 s[4:5], -1
	s_cbranch_scc0 .LBB0_809
	s_mov_b64 s[4:5], s[56:57]
	v_mov_b32_e32 v1, v0
	s_load_dwordx2 s[8:9], s[4:5], 0xf0
	v_readlane_b32 s4, v252, 8
	v_mbcnt_lo_u32_b32 v1, -1, v1
	v_mbcnt_hi_u32_b32 v1, -1, v1
	v_add_u32_e32 v1, s4, v1
	s_mov_b64 s[10:11], s[56:57]
	s_add_i32 s7, s3, 0xfffffc00
	s_lshr_b32 s4, s7, 5
	s_load_dwordx2 s[10:11], s[10:11], 0xf0
	s_lshl_b32 s12, s4, 11
	s_mul_i32 s13, s4, 0x3000000
	s_mul_hi_u32 s12, s12, 0x6000
	s_waitcnt lgkmcnt(0)
	s_add_u32 s13, s8, s13
	s_addc_u32 s12, s9, s12
	s_lshl_b32 s8, s7, 3
	s_lshl_b32 s36, s4, 8
	s_and_b32 s14, s8, 0xc0
	s_lshl_b64 s[8:9], s[36:37], 12
	s_add_u32 s8, s10, s8
	s_addc_u32 s9, s11, s9
	s_lshl_b32 s10, s22, 1
	s_add_u32 s8, s8, s10
	s_addc_u32 s9, s9, 0
	s_lshl_b32 s36, s14, 1
	s_add_u32 s8, s8, s36
	s_addc_u32 s9, s9, 0
	v_readfirstlane_b32 s5, v1
	s_add_u32 s8, s8, 0x3f500000
	s_addc_u32 s9, s9, 0
	s_lshl_b32 s7, s7, 8
	s_ashr_i32 s10, s5, 1
	s_and_b32 s7, s7, 0x700
	s_andn2_b32 s10, s10, 31
	s_add_i32 s7, s10, s7
	s_add_u32 s10, s13, s36
	s_addc_u32 s11, s12, 0
	s_add_u32 s10, s10, 0x3fd03e00
	s_addc_u32 s11, s11, 0
	v_and_or_b32 v78, v1, 31, s7
	v_mov_b64_e32 v[2:3], s[10:11]
	s_movk_i32 s7, 0x6000
	v_bfe_u32 v4, v1, 5, 1
	v_mad_i64_i32 v[2:3], s[10:11], v78, s7, v[2:3]
	v_lshlrev_b32_e32 v6, 4, v4
	v_mov_b32_e32 v7, v0
	v_lshl_add_u64 v[2:3], v[2:3], 0, v[6:7]
	global_load_dwordx4 v[160:163], v[2:3], off
	global_load_dwordx4 v[148:151], v[2:3], off offset:32
	global_load_dwordx4 v[152:155], v[2:3], off offset:64
	global_load_dwordx4 v[156:159], v[2:3], off offset:96
	s_ashr_i32 s5, s5, 6
	s_lshl_b32 s7, s5, 12
	v_and_b32_e32 v5, 63, v1
	s_add_i32 s7, s7, 0
	s_add_i32 s7, s7, 0x1a980
	v_lshlrev_b32_e32 v5, 4, v5
	v_add_u32_e32 v79, s7, v5
	v_lshlrev_b32_e32 v5, 4, v1
	v_xor_b32_e32 v5, v5, v1
	s_cmp_lt_i32 s5, 4
	v_ashrrev_i32_e32 v2, 3, v1
	v_lshlrev_b32_e32 v3, 7, v2
	v_and_or_b32 v5, v5, s40, v3
	v_ashrrev_i32_e32 v3, 31, v2
	v_lshlrev_b64 v[2:3], 12, v[2:3]
	v_lshl_add_u64 v[2:3], s[8:9], 0, v[2:3]
	v_add_u32_e32 v87, 0, v5
	v_lshlrev_b32_e32 v6, 3, v1
	v_and_b32_e32 v6, 56, v6
	v_lshlrev_b32_e32 v6, 1, v6
	v_mov_b32_e32 v7, v0
	v_lshl_add_u64 v[42:43], v[2:3], 0, v[6:7]
	v_ashrrev_i32_e32 v2, 31, v1
	v_lshrrev_b32_e32 v2, 29, v2
	v_add_u32_e32 v2, v1, v2
	v_ashrrev_i32_e32 v18, 3, v2
	v_and_b32_e32 v2, -8, v2
	v_sub_u32_e32 v22, v1, v2
	v_ashrrev_i32_e32 v19, 31, v18
	global_load_dwordx4 v[6:9], v[42:43], off
	v_lshlrev_b64 v[44:45], 12, v[18:19]
	v_lshlrev_b32_e32 v2, 3, v22
	v_lshl_add_u64 v[10:11], s[8:9], 0, v[44:45]
	v_ashrrev_i32_e32 v3, 31, v2
	v_lshl_add_u64 v[20:21], v[2:3], 1, v[10:11]
	v_add_co_u32_e32 v14, vcc, s67, v42
	global_load_dwordx4 v[10:13], v[20:21], off offset:512
	s_nop 0
	v_addc_co_u32_e32 v15, vcc, 0, v43, vcc
	global_load_dwordx4 v[14:17], v[14:15], off
	v_mul_lo_u32 v5, v18, s34
	v_add_u32_e32 v5, 0, v5
	s_waitcnt vmcnt(6)
	ds_write_b128 v79, v[160:163]
	s_waitcnt vmcnt(5)
	ds_write_b128 v79, v[148:151] offset:1024
	s_waitcnt vmcnt(4)
	ds_write_b128 v79, v[152:155] offset:2048
	s_waitcnt vmcnt(3)
	ds_write_b128 v79, v[156:159] offset:3072
	s_waitcnt vmcnt(2)
	ds_write_b128 v87, v[6:9]
	v_lshlrev_b32_e32 v6, 4, v22
	v_add_u32_e32 v81, v5, v6
	v_add_co_u32_e32 v6, vcc, 0x80000, v42
	s_waitcnt vmcnt(1)
	ds_write_b128 v81, v[10:13] offset:24576
	s_waitcnt vmcnt(0)
	ds_write_b128 v87, v[14:17] offset:8192
	v_addc_co_u32_e32 v7, vcc, 0, v43, vcc
	s_waitcnt lgkmcnt(0)
	s_barrier
	global_load_dwordx4 v[34:37], v[6:7], off
	v_add_co_u32_e32 v6, vcc, 0x40000, v20
	s_nop 1
	v_addc_co_u32_e32 v7, vcc, 0, v21, vcc
	global_load_dwordx4 v[38:41], v[6:7], off offset:512
	s_cbranch_scc1 .LBB0_800
	s_barrier

.LBB0_809:
	s_and_b64 vcc, exec, s[4:5]
	s_cbranch_vccz .LBB0_822
	s_mov_b64 s[4:5], s[56:57]
	s_load_dwordx2 s[8:9], s[4:5], 0xf0
	v_mov_b32_e32 v1, v0
	s_lshr_b32 s7, s3, 7
	v_mbcnt_lo_u32_b32 v1, -1, v1
	s_mul_i32 s36, s7, 0x1800000
	v_mbcnt_hi_u32_b32 v1, -1, v1
	v_readlane_b32 s4, v252, 8
	s_bfe_u32 s18, s3, 0x40003
	s_lshl_b64 s[10:11], s[36:37], 1
	v_add_u32_e32 v12, s4, v1
	s_waitcnt lgkmcnt(0)
	s_add_u32 s4, s8, s10
	s_addc_u32 s5, s9, s11
	s_add_u32 s12, s4, 0x3fd00000
	s_addc_u32 s13, s5, 0
	s_lshl_b32 s4, s18, 7
	s_add_u32 s4, s12, s4
	s_addc_u32 s5, s13, 0
	s_add_u32 s4, s4, 0x1a00
	s_addc_u32 s5, s5, 0
	s_lshl_b32 s14, s3, 8
	s_and_b32 s20, s14, 0x700
	v_readfirstlane_b32 s27, v12
	s_ashr_i32 s21, s27, 1
	s_lshr_b32 s16, s20, 6
	s_andn2_b32 s21, s21, 31
	s_max_u32 s19, s16, 2
	s_min_u32 s14, s16, 26
	s_lshl_b32 s25, s3, 2
	s_add_i32 s26, s21, s20
	s_sub_i32 s23, s14, s19
	s_and_b32 s24, s25, 0x180
	s_add_u32 s3, s12, s24
	v_sub_u32_e64 v8, s16, 2 clamp
	s_mov_b64 s[16:17], s[56:57]
	s_addc_u32 s15, s13, 0
	s_add_u32 s12, s3, 0x2200
	s_load_dwordx2 s[16:17], s[16:17], 0x78
	s_addc_u32 s13, s15, 0
	s_add_u32 s14, s3, 0x2400
	s_addc_u32 s15, s15, 0
	s_or_b32 s36, s18, s6
	s_lshl_b64 s[28:29], s[36:37], 2
	s_waitcnt lgkmcnt(0)
	s_add_u32 s16, s16, s28
	v_and_b32_e32 v1, 31, v12
	s_addc_u32 s17, s17, s29
	v_or_b32_e32 v106, s26, v1
	global_load_dword v13, v0, s[16:17]
	v_mov_b64_e32 v[2:3], s[4:5]
	s_movk_i32 s16, 0x6000
	v_mad_i64_i32 v[2:3], s[4:5], v106, s16, v[2:3]
	s_ashr_i32 s3, s27, 6
	s_lshl_b32 s4, s3, 12
	v_and_b32_e32 v4, 63, v12
	s_add_i32 s4, s4, 0
	v_bfe_u32 v115, v12, 5, 1
	s_add_i32 s4, s4, 0x1a980
	v_lshlrev_b32_e32 v4, 4, v4
	v_add_u32_e32 v107, s4, v4
	v_lshlrev_b32_e32 v4, 4, v115
	v_mov_b32_e32 v5, v0
	v_lshl_add_u64 v[6:7], v[2:3], 0, v[4:5]
	global_load_dwordx4 v[160:163], v[6:7], off
	global_load_dwordx4 v[148:151], v[6:7], off offset:32
	global_load_dwordx4 v[152:155], v[6:7], off offset:64
	global_load_dwordx4 v[156:159], v[6:7], off offset:96
	v_ashrrev_i32_e32 v108, 3, v12
	v_lshlrev_b32_e32 v8, 6, v8
	v_mov_b32_e32 v9, v0
	v_ashrrev_i32_e32 v109, 31, v108
	v_mov_b32_e32 v11, v0
	v_mov_b64_e32 v[16:17], s[14:15]
	s_cmp_gt_i32 s23, -7
	v_ashrrev_i32_e32 v6, 31, v12
	v_lshrrev_b32_e32 v6, 29, v6
	v_add_u32_e32 v7, v12, v6
	v_ashrrev_i32_e32 v6, 3, v7
	v_and_b32_e32 v7, -8, v7
	v_sub_u32_e32 v14, v12, v7
	v_ashrrev_i32_e32 v7, 31, v6
	v_lshl_add_u64 v[2:3], v[8:9], 0, v[108:109]
	v_mov_b64_e32 v[4:5], s[12:13]
	v_mad_u64_u32 v[4:5], s[4:5], v2, s16, v[4:5]
	v_lshlrev_b32_e32 v2, 3, v12
	v_and_b32_e32 v2, 56, v2
	v_mad_i32_i24 v5, v3, s16, v5
	v_lshlrev_b32_e32 v10, 1, v2
	v_lshl_add_u64 v[8:9], v[8:9], 0, v[6:7]
	v_lshl_add_u64 v[2:3], v[4:5], 0, v[10:11]
	v_mad_u64_u32 v[16:17], s[4:5], v8, s16, v[16:17]
	v_lshlrev_b32_e32 v8, 3, v14
	global_load_dwordx4 v[2:5], v[2:3], off
	v_mad_i32_i24 v17, v9, s16, v17
	v_ashrrev_i32_e32 v9, 31, v8
	v_lshl_add_u64 v[16:17], v[8:9], 1, v[16:17]
	global_load_dwordx4 v[98:101], v[16:17], off
	s_cselect_b64 s[16:17], -1, 0
	s_cmp_lt_i32 s23, -6
	s_waitcnt vmcnt(5)
	ds_write_b128 v107, v[160:163]
	s_waitcnt vmcnt(4)
	ds_write_b128 v107, v[148:151] offset:1024
	s_waitcnt vmcnt(3)
	ds_write_b128 v107, v[152:155] offset:2048
	s_waitcnt vmcnt(2)
	ds_write_b128 v107, v[156:159] offset:3072
	s_waitcnt vmcnt(1)
	v_mov_b64_e32 v[104:105], v[4:5]
	v_mov_b64_e32 v[102:103], v[2:3]
	s_cbranch_scc1 .LBB0_812
	s_add_i32 s36, s19, -1
	s_lshl_b64 s[4:5], s[36:37], 6
	v_lshl_add_u64 v[16:17], s[4:5], 0, v[108:109]
	v_mov_b64_e32 v[18:19], s[12:13]
	s_movk_i32 s27, 0x6000
	v_mad_u64_u32 v[18:19], s[4:5], v16, s27, v[18:19]
	v_mad_i32_i24 v19, v17, s27, v19
	v_lshl_add_u64 v[16:17], v[18:19], 0, v[10:11]
	global_load_dwordx4 v[102:105], v[16:17], off
